# P1 gate epilogue (8 of 12 units) rewritten by hand: instruction selection - bias and -log2e folded into packed fma, packed +1.0, u8 packing via SDWA byte writes, saddr stores
# baseline (speedup 1.0000x reference)
.LBB0_220:
	s_cmp_lt_i32 s84, 3
	s_cbranch_scc1 .LBB0_262
	s_cmp_lg_u32 s84, 3
	s_cbranch_scc0 .LBB0_223
	s_add_i32 s16, s84, -4
	s_add_i32 vcc_lo, s84, -8
	s_lshl_b32 s48, s16, 8
	s_cmp_lt_u32 s84, 8
	s_cselect_b32 s4, s30, s66
	s_cselect_b32 s5, s31, s67
	s_cselect_b32 vcc_lo, s16, vcc_lo
	s_lshl_b32 vcc_lo, vcc_lo, 8
	s_mov_b32 s98, 0xbfb8aa3b
	v_lshl_add_u64 v[132:133], s[48:49], 2, v[186:187]
	global_load_dwordx4 v[136:139], v[132:133], off
	global_load_dwordx4 v[140:143], v[132:133], off offset:16
	global_load_dwordx4 v[144:147], v[132:133], off offset:512
	global_load_dwordx4 v[148:151], v[132:133], off offset:528
	v_lshl_add_u32 v152, v198, 10, v178
	v_add_u32_e32 v152, vcc_lo, v152
	v_add_u32_e32 v153, 0x4000, v152
	v_add_u32_e32 v154, 0x8000, v152
	v_add_u32_e32 v155, 0xc000, v152
	v_add_u32_e32 v156, 0x20000, v152
	v_add_u32_e32 v157, 0x24000, v152
	v_add_u32_e32 v158, 0x28000, v152
	v_add_u32_e32 v159, 0x2c000, v152
	s_waitcnt vmcnt(0)
	v_mul_f32_e32 v136, 0xbfb8aa3b, v136
	v_mul_f32_e32 v137, 0xbfb8aa3b, v137
	v_mul_f32_e32 v138, 0xbfb8aa3b, v138
	v_mul_f32_e32 v139, 0xbfb8aa3b, v139
	v_mul_f32_e32 v140, 0xbfb8aa3b, v140
	v_mul_f32_e32 v141, 0xbfb8aa3b, v141
	v_mul_f32_e32 v142, 0xbfb8aa3b, v142
	v_mul_f32_e32 v143, 0xbfb8aa3b, v143
	v_mul_f32_e32 v144, 0xbfb8aa3b, v144
	v_mul_f32_e32 v145, 0xbfb8aa3b, v145
	v_mul_f32_e32 v146, 0xbfb8aa3b, v146
	v_mul_f32_e32 v147, 0xbfb8aa3b, v147
	v_mul_f32_e32 v148, 0xbfb8aa3b, v148
	v_mul_f32_e32 v149, 0xbfb8aa3b, v149
	v_mul_f32_e32 v150, 0xbfb8aa3b, v150
	v_mul_f32_e32 v151, 0xbfb8aa3b, v151
	v_pk_fma_f32 v[120:121], v[120:121], s[98:99], v[136:137] op_sel_hi:[1,0,1]
	v_pk_fma_f32 v[122:123], v[122:123], s[98:99], v[138:139] op_sel_hi:[1,0,1]
	v_pk_fma_f32 v[124:125], v[124:125], s[98:99], v[140:141] op_sel_hi:[1,0,1]
	v_pk_fma_f32 v[126:127], v[126:127], s[98:99], v[142:143] op_sel_hi:[1,0,1]
	v_exp_f32_e32 v120, v120
	v_exp_f32_e32 v121, v121
	v_exp_f32_e32 v122, v122
	v_exp_f32_e32 v123, v123
	v_exp_f32_e32 v124, v124
	v_exp_f32_e32 v125, v125
	v_exp_f32_e32 v126, v126
	v_exp_f32_e32 v127, v127
	v_pk_add_f32 v[120:121], v[120:121], 1.0 op_sel_hi:[1,0]
	v_pk_add_f32 v[122:123], v[122:123], 1.0 op_sel_hi:[1,0]
	v_pk_add_f32 v[124:125], v[124:125], 1.0 op_sel_hi:[1,0]
	v_pk_add_f32 v[126:127], v[126:127], 1.0 op_sel_hi:[1,0]
	v_rcp_f32_e32 v120, v120
	v_rcp_f32_e32 v121, v121
	v_rcp_f32_e32 v122, v122
	v_rcp_f32_e32 v123, v123
	v_rcp_f32_e32 v124, v124
	v_rcp_f32_e32 v125, v125
	v_rcp_f32_e32 v126, v126
	v_rcp_f32_e32 v127, v127
	v_pk_fma_f32 v[120:121], v[120:121], s[20:21], 0.5 op_sel_hi:[1,0,0]
	v_pk_fma_f32 v[122:123], v[122:123], s[20:21], 0.5 op_sel_hi:[1,0,0]
	v_pk_fma_f32 v[124:125], v[124:125], s[20:21], 0.5 op_sel_hi:[1,0,0]
	v_pk_fma_f32 v[126:127], v[126:127], s[20:21], 0.5 op_sel_hi:[1,0,0]
	v_cvt_u32_f32_e32 v160, v120
	v_cvt_u32_f32_e32 v161, v124
	v_cvt_u32_f32_sdwa v160, v121 dst_sel:BYTE_1 dst_unused:UNUSED_PRESERVE src0_sel:DWORD
	v_cvt_u32_f32_sdwa v161, v125 dst_sel:BYTE_1 dst_unused:UNUSED_PRESERVE src0_sel:DWORD
	v_cvt_u32_f32_sdwa v160, v122 dst_sel:BYTE_2 dst_unused:UNUSED_PRESERVE src0_sel:DWORD
	v_cvt_u32_f32_sdwa v161, v126 dst_sel:BYTE_2 dst_unused:UNUSED_PRESERVE src0_sel:DWORD
	v_cvt_u32_f32_sdwa v160, v123 dst_sel:BYTE_3 dst_unused:UNUSED_PRESERVE src0_sel:DWORD
	v_cvt_u32_f32_sdwa v161, v127 dst_sel:BYTE_3 dst_unused:UNUSED_PRESERVE src0_sel:DWORD
	s_nop 0
	global_store_dwordx2 v152, v[160:161], s[4:5]
	v_pk_fma_f32 v[116:117], v[116:117], s[98:99], v[144:145] op_sel_hi:[1,0,1]
	v_pk_fma_f32 v[118:119], v[118:119], s[98:99], v[146:147] op_sel_hi:[1,0,1]
	v_pk_fma_f32 v[112:113], v[112:113], s[98:99], v[148:149] op_sel_hi:[1,0,1]
	v_pk_fma_f32 v[114:115], v[114:115], s[98:99], v[150:151] op_sel_hi:[1,0,1]
	v_exp_f32_e32 v116, v116
	v_exp_f32_e32 v117, v117
	v_exp_f32_e32 v118, v118
	v_exp_f32_e32 v119, v119
	v_exp_f32_e32 v112, v112
	v_exp_f32_e32 v113, v113
	v_exp_f32_e32 v114, v114
	v_exp_f32_e32 v115, v115
	v_pk_add_f32 v[116:117], v[116:117], 1.0 op_sel_hi:[1,0]
	v_pk_add_f32 v[118:119], v[118:119], 1.0 op_sel_hi:[1,0]
	v_pk_add_f32 v[112:113], v[112:113], 1.0 op_sel_hi:[1,0]
	v_pk_add_f32 v[114:115], v[114:115], 1.0 op_sel_hi:[1,0]
	v_rcp_f32_e32 v116, v116
	v_rcp_f32_e32 v117, v117
	v_rcp_f32_e32 v118, v118
	v_rcp_f32_e32 v119, v119
	v_rcp_f32_e32 v112, v112
	v_rcp_f32_e32 v113, v113
	v_rcp_f32_e32 v114, v114
	v_rcp_f32_e32 v115, v115
	v_pk_fma_f32 v[116:117], v[116:117], s[20:21], 0.5 op_sel_hi:[1,0,0]
	v_pk_fma_f32 v[118:119], v[118:119], s[20:21], 0.5 op_sel_hi:[1,0,0]
	v_pk_fma_f32 v[112:113], v[112:113], s[20:21], 0.5 op_sel_hi:[1,0,0]
	v_pk_fma_f32 v[114:115], v[114:115], s[20:21], 0.5 op_sel_hi:[1,0,0]
	v_cvt_u32_f32_e32 v134, v116
	v_cvt_u32_f32_e32 v135, v112
	v_cvt_u32_f32_sdwa v134, v117 dst_sel:BYTE_1 dst_unused:UNUSED_PRESERVE src0_sel:DWORD
	v_cvt_u32_f32_sdwa v135, v113 dst_sel:BYTE_1 dst_unused:UNUSED_PRESERVE src0_sel:DWORD
	v_cvt_u32_f32_sdwa v134, v118 dst_sel:BYTE_2 dst_unused:UNUSED_PRESERVE src0_sel:DWORD
	v_cvt_u32_f32_sdwa v135, v114 dst_sel:BYTE_2 dst_unused:UNUSED_PRESERVE src0_sel:DWORD
	v_cvt_u32_f32_sdwa v134, v119 dst_sel:BYTE_3 dst_unused:UNUSED_PRESERVE src0_sel:DWORD
	v_cvt_u32_f32_sdwa v135, v115 dst_sel:BYTE_3 dst_unused:UNUSED_PRESERVE src0_sel:DWORD
	s_nop 0
	global_store_dwordx2 v152, v[134:135], s[4:5] offset:128
	v_pk_fma_f32 v[108:109], v[108:109], s[98:99], v[136:137] op_sel_hi:[1,0,1]
	v_pk_fma_f32 v[110:111], v[110:111], s[98:99], v[138:139] op_sel_hi:[1,0,1]
	v_pk_fma_f32 v[104:105], v[104:105], s[98:99], v[140:141] op_sel_hi:[1,0,1]
	v_pk_fma_f32 v[106:107], v[106:107], s[98:99], v[142:143] op_sel_hi:[1,0,1]
	v_exp_f32_e32 v108, v108
	v_exp_f32_e32 v109, v109
	v_exp_f32_e32 v110, v110
	v_exp_f32_e32 v111, v111
	v_exp_f32_e32 v104, v104
	v_exp_f32_e32 v105, v105
	v_exp_f32_e32 v106, v106
	v_exp_f32_e32 v107, v107
	v_pk_add_f32 v[108:109], v[108:109], 1.0 op_sel_hi:[1,0]
	v_pk_add_f32 v[110:111], v[110:111], 1.0 op_sel_hi:[1,0]
	v_pk_add_f32 v[104:105], v[104:105], 1.0 op_sel_hi:[1,0]
	v_pk_add_f32 v[106:107], v[106:107], 1.0 op_sel_hi:[1,0]
	v_rcp_f32_e32 v108, v108
	v_rcp_f32_e32 v109, v109
	v_rcp_f32_e32 v110, v110
	v_rcp_f32_e32 v111, v111
	v_rcp_f32_e32 v104, v104
	v_rcp_f32_e32 v105, v105
	v_rcp_f32_e32 v106, v106
	v_rcp_f32_e32 v107, v107
	v_pk_fma_f32 v[108:109], v[108:109], s[20:21], 0.5 op_sel_hi:[1,0,0]
	v_pk_fma_f32 v[110:111], v[110:111], s[20:21], 0.5 op_sel_hi:[1,0,0]
	v_pk_fma_f32 v[104:105], v[104:105], s[20:21], 0.5 op_sel_hi:[1,0,0]
	v_pk_fma_f32 v[106:107], v[106:107], s[20:21], 0.5 op_sel_hi:[1,0,0]
	v_cvt_u32_f32_e32 v160, v108
	v_cvt_u32_f32_e32 v161, v104
	v_cvt_u32_f32_sdwa v160, v109 dst_sel:BYTE_1 dst_unused:UNUSED_PRESERVE src0_sel:DWORD
	v_cvt_u32_f32_sdwa v161, v105 dst_sel:BYTE_1 dst_unused:UNUSED_PRESERVE src0_sel:DWORD
	v_cvt_u32_f32_sdwa v160, v110 dst_sel:BYTE_2 dst_unused:UNUSED_PRESERVE src0_sel:DWORD
	v_cvt_u32_f32_sdwa v161, v106 dst_sel:BYTE_2 dst_unused:UNUSED_PRESERVE src0_sel:DWORD
	v_cvt_u32_f32_sdwa v160, v111 dst_sel:BYTE_3 dst_unused:UNUSED_PRESERVE src0_sel:DWORD
	v_cvt_u32_f32_sdwa v161, v107 dst_sel:BYTE_3 dst_unused:UNUSED_PRESERVE src0_sel:DWORD
	s_nop 0
	global_store_dwordx2 v153, v[160:161], s[4:5]
	v_pk_fma_f32 v[100:101], v[100:101], s[98:99], v[144:145] op_sel_hi:[1,0,1]
	v_pk_fma_f32 v[102:103], v[102:103], s[98:99], v[146:147] op_sel_hi:[1,0,1]
	v_pk_fma_f32 v[96:97], v[96:97], s[98:99], v[148:149] op_sel_hi:[1,0,1]
	v_pk_fma_f32 v[98:99], v[98:99], s[98:99], v[150:151] op_sel_hi:[1,0,1]
	v_exp_f32_e32 v100, v100
	v_exp_f32_e32 v101, v101
	v_exp_f32_e32 v102, v102
	v_exp_f32_e32 v103, v103
	v_exp_f32_e32 v96, v96
	v_exp_f32_e32 v97, v97
	v_exp_f32_e32 v98, v98
	v_exp_f32_e32 v99, v99
	v_pk_add_f32 v[100:101], v[100:101], 1.0 op_sel_hi:[1,0]
	v_pk_add_f32 v[102:103], v[102:103], 1.0 op_sel_hi:[1,0]
	v_pk_add_f32 v[96:97], v[96:97], 1.0 op_sel_hi:[1,0]
	v_pk_add_f32 v[98:99], v[98:99], 1.0 op_sel_hi:[1,0]
	v_rcp_f32_e32 v100, v100
	v_rcp_f32_e32 v101, v101
	v_rcp_f32_e32 v102, v102
	v_rcp_f32_e32 v103, v103
	v_rcp_f32_e32 v96, v96
	v_rcp_f32_e32 v97, v97
	v_rcp_f32_e32 v98, v98
	v_rcp_f32_e32 v99, v99
	v_pk_fma_f32 v[100:101], v[100:101], s[20:21], 0.5 op_sel_hi:[1,0,0]
	v_pk_fma_f32 v[102:103], v[102:103], s[20:21], 0.5 op_sel_hi:[1,0,0]
	v_pk_fma_f32 v[96:97], v[96:97], s[20:21], 0.5 op_sel_hi:[1,0,0]
	v_pk_fma_f32 v[98:99], v[98:99], s[20:21], 0.5 op_sel_hi:[1,0,0]
	v_cvt_u32_f32_e32 v134, v100
	v_cvt_u32_f32_e32 v135, v96
	v_cvt_u32_f32_sdwa v134, v101 dst_sel:BYTE_1 dst_unused:UNUSED_PRESERVE src0_sel:DWORD
	v_cvt_u32_f32_sdwa v135, v97 dst_sel:BYTE_1 dst_unused:UNUSED_PRESERVE src0_sel:DWORD
	v_cvt_u32_f32_sdwa v134, v102 dst_sel:BYTE_2 dst_unused:UNUSED_PRESERVE src0_sel:DWORD
	v_cvt_u32_f32_sdwa v135, v98 dst_sel:BYTE_2 dst_unused:UNUSED_PRESERVE src0_sel:DWORD
	v_cvt_u32_f32_sdwa v134, v103 dst_sel:BYTE_3 dst_unused:UNUSED_PRESERVE src0_sel:DWORD
	v_cvt_u32_f32_sdwa v135, v99 dst_sel:BYTE_3 dst_unused:UNUSED_PRESERVE src0_sel:DWORD
	s_nop 0
	global_store_dwordx2 v153, v[134:135], s[4:5] offset:128
	v_pk_fma_f32 v[92:93], v[92:93], s[98:99], v[136:137] op_sel_hi:[1,0,1]
	v_pk_fma_f32 v[94:95], v[94:95], s[98:99], v[138:139] op_sel_hi:[1,0,1]
	v_pk_fma_f32 v[88:89], v[88:89], s[98:99], v[140:141] op_sel_hi:[1,0,1]
	v_pk_fma_f32 v[90:91], v[90:91], s[98:99], v[142:143] op_sel_hi:[1,0,1]
	v_exp_f32_e32 v92, v92
	v_exp_f32_e32 v93, v93
	v_exp_f32_e32 v94, v94
	v_exp_f32_e32 v95, v95
	v_exp_f32_e32 v88, v88
	v_exp_f32_e32 v89, v89
	v_exp_f32_e32 v90, v90
	v_exp_f32_e32 v91, v91
	v_pk_add_f32 v[92:93], v[92:93], 1.0 op_sel_hi:[1,0]
	v_pk_add_f32 v[94:95], v[94:95], 1.0 op_sel_hi:[1,0]
	v_pk_add_f32 v[88:89], v[88:89], 1.0 op_sel_hi:[1,0]
	v_pk_add_f32 v[90:91], v[90:91], 1.0 op_sel_hi:[1,0]
	v_rcp_f32_e32 v92, v92
	v_rcp_f32_e32 v93, v93
	v_rcp_f32_e32 v94, v94
	v_rcp_f32_e32 v95, v95
	v_rcp_f32_e32 v88, v88
	v_rcp_f32_e32 v89, v89
	v_rcp_f32_e32 v90, v90
	v_rcp_f32_e32 v91, v91
	v_pk_fma_f32 v[92:93], v[92:93], s[20:21], 0.5 op_sel_hi:[1,0,0]
	v_pk_fma_f32 v[94:95], v[94:95], s[20:21], 0.5 op_sel_hi:[1,0,0]
	v_pk_fma_f32 v[88:89], v[88:89], s[20:21], 0.5 op_sel_hi:[1,0,0]
	v_pk_fma_f32 v[90:91], v[90:91], s[20:21], 0.5 op_sel_hi:[1,0,0]
	v_cvt_u32_f32_e32 v160, v92
	v_cvt_u32_f32_e32 v161, v88
	v_cvt_u32_f32_sdwa v160, v93 dst_sel:BYTE_1 dst_unused:UNUSED_PRESERVE src0_sel:DWORD
	v_cvt_u32_f32_sdwa v161, v89 dst_sel:BYTE_1 dst_unused:UNUSED_PRESERVE src0_sel:DWORD
	v_cvt_u32_f32_sdwa v160, v94 dst_sel:BYTE_2 dst_unused:UNUSED_PRESERVE src0_sel:DWORD
	v_cvt_u32_f32_sdwa v161, v90 dst_sel:BYTE_2 dst_unused:UNUSED_PRESERVE src0_sel:DWORD
	v_cvt_u32_f32_sdwa v160, v95 dst_sel:BYTE_3 dst_unused:UNUSED_PRESERVE src0_sel:DWORD
	v_cvt_u32_f32_sdwa v161, v91 dst_sel:BYTE_3 dst_unused:UNUSED_PRESERVE src0_sel:DWORD
	s_nop 0
	global_store_dwordx2 v154, v[160:161], s[4:5]
	v_pk_fma_f32 v[84:85], v[84:85], s[98:99], v[144:145] op_sel_hi:[1,0,1]
	v_pk_fma_f32 v[86:87], v[86:87], s[98:99], v[146:147] op_sel_hi:[1,0,1]
	v_pk_fma_f32 v[80:81], v[80:81], s[98:99], v[148:149] op_sel_hi:[1,0,1]
	v_pk_fma_f32 v[82:83], v[82:83], s[98:99], v[150:151] op_sel_hi:[1,0,1]
	v_exp_f32_e32 v84, v84
	v_exp_f32_e32 v85, v85
	v_exp_f32_e32 v86, v86
	v_exp_f32_e32 v87, v87
	v_exp_f32_e32 v80, v80
	v_exp_f32_e32 v81, v81
	v_exp_f32_e32 v82, v82
	v_exp_f32_e32 v83, v83
	v_pk_add_f32 v[84:85], v[84:85], 1.0 op_sel_hi:[1,0]
	v_pk_add_f32 v[86:87], v[86:87], 1.0 op_sel_hi:[1,0]
	v_pk_add_f32 v[80:81], v[80:81], 1.0 op_sel_hi:[1,0]
	v_pk_add_f32 v[82:83], v[82:83], 1.0 op_sel_hi:[1,0]
	v_rcp_f32_e32 v84, v84
	v_rcp_f32_e32 v85, v85
	v_rcp_f32_e32 v86, v86
	v_rcp_f32_e32 v87, v87
	v_rcp_f32_e32 v80, v80
	v_rcp_f32_e32 v81, v81
	v_rcp_f32_e32 v82, v82
	v_rcp_f32_e32 v83, v83
	v_pk_fma_f32 v[84:85], v[84:85], s[20:21], 0.5 op_sel_hi:[1,0,0]
	v_pk_fma_f32 v[86:87], v[86:87], s[20:21], 0.5 op_sel_hi:[1,0,0]
	v_pk_fma_f32 v[80:81], v[80:81], s[20:21], 0.5 op_sel_hi:[1,0,0]
	v_pk_fma_f32 v[82:83], v[82:83], s[20:21], 0.5 op_sel_hi:[1,0,0]
	v_cvt_u32_f32_e32 v134, v84
	v_cvt_u32_f32_e32 v135, v80
	v_cvt_u32_f32_sdwa v134, v85 dst_sel:BYTE_1 dst_unused:UNUSED_PRESERVE src0_sel:DWORD
	v_cvt_u32_f32_sdwa v135, v81 dst_sel:BYTE_1 dst_unused:UNUSED_PRESERVE src0_sel:DWORD
	v_cvt_u32_f32_sdwa v134, v86 dst_sel:BYTE_2 dst_unused:UNUSED_PRESERVE src0_sel:DWORD
	v_cvt_u32_f32_sdwa v135, v82 dst_sel:BYTE_2 dst_unused:UNUSED_PRESERVE src0_sel:DWORD
	v_cvt_u32_f32_sdwa v134, v87 dst_sel:BYTE_3 dst_unused:UNUSED_PRESERVE src0_sel:DWORD
	v_cvt_u32_f32_sdwa v135, v83 dst_sel:BYTE_3 dst_unused:UNUSED_PRESERVE src0_sel:DWORD
	s_nop 0
	global_store_dwordx2 v154, v[134:135], s[4:5] offset:128
	v_pk_fma_f32 v[76:77], v[76:77], s[98:99], v[136:137] op_sel_hi:[1,0,1]
	v_pk_fma_f32 v[78:79], v[78:79], s[98:99], v[138:139] op_sel_hi:[1,0,1]
	v_pk_fma_f32 v[72:73], v[72:73], s[98:99], v[140:141] op_sel_hi:[1,0,1]
	v_pk_fma_f32 v[74:75], v[74:75], s[98:99], v[142:143] op_sel_hi:[1,0,1]
	v_exp_f32_e32 v76, v76
	v_exp_f32_e32 v77, v77
	v_exp_f32_e32 v78, v78
	v_exp_f32_e32 v79, v79
	v_exp_f32_e32 v72, v72
	v_exp_f32_e32 v73, v73
	v_exp_f32_e32 v74, v74
	v_exp_f32_e32 v75, v75
	v_pk_add_f32 v[76:77], v[76:77], 1.0 op_sel_hi:[1,0]
	v_pk_add_f32 v[78:79], v[78:79], 1.0 op_sel_hi:[1,0]
	v_pk_add_f32 v[72:73], v[72:73], 1.0 op_sel_hi:[1,0]
	v_pk_add_f32 v[74:75], v[74:75], 1.0 op_sel_hi:[1,0]
	v_rcp_f32_e32 v76, v76
	v_rcp_f32_e32 v77, v77
	v_rcp_f32_e32 v78, v78
	v_rcp_f32_e32 v79, v79
	v_rcp_f32_e32 v72, v72
	v_rcp_f32_e32 v73, v73
	v_rcp_f32_e32 v74, v74
	v_rcp_f32_e32 v75, v75
	v_pk_fma_f32 v[76:77], v[76:77], s[20:21], 0.5 op_sel_hi:[1,0,0]
	v_pk_fma_f32 v[78:79], v[78:79], s[20:21], 0.5 op_sel_hi:[1,0,0]
	v_pk_fma_f32 v[72:73], v[72:73], s[20:21], 0.5 op_sel_hi:[1,0,0]
	v_pk_fma_f32 v[74:75], v[74:75], s[20:21], 0.5 op_sel_hi:[1,0,0]
	v_cvt_u32_f32_e32 v160, v76
	v_cvt_u32_f32_e32 v161, v72
	v_cvt_u32_f32_sdwa v160, v77 dst_sel:BYTE_1 dst_unused:UNUSED_PRESERVE src0_sel:DWORD
	v_cvt_u32_f32_sdwa v161, v73 dst_sel:BYTE_1 dst_unused:UNUSED_PRESERVE src0_sel:DWORD
	v_cvt_u32_f32_sdwa v160, v78 dst_sel:BYTE_2 dst_unused:UNUSED_PRESERVE src0_sel:DWORD
	v_cvt_u32_f32_sdwa v161, v74 dst_sel:BYTE_2 dst_unused:UNUSED_PRESERVE src0_sel:DWORD
	v_cvt_u32_f32_sdwa v160, v79 dst_sel:BYTE_3 dst_unused:UNUSED_PRESERVE src0_sel:DWORD
	v_cvt_u32_f32_sdwa v161, v75 dst_sel:BYTE_3 dst_unused:UNUSED_PRESERVE src0_sel:DWORD
	s_nop 0
	global_store_dwordx2 v155, v[160:161], s[4:5]
	v_pk_fma_f32 v[68:69], v[68:69], s[98:99], v[144:145] op_sel_hi:[1,0,1]
	v_pk_fma_f32 v[70:71], v[70:71], s[98:99], v[146:147] op_sel_hi:[1,0,1]
	v_pk_fma_f32 v[64:65], v[64:65], s[98:99], v[148:149] op_sel_hi:[1,0,1]
	v_pk_fma_f32 v[66:67], v[66:67], s[98:99], v[150:151] op_sel_hi:[1,0,1]
	v_exp_f32_e32 v68, v68
	v_exp_f32_e32 v69, v69
	v_exp_f32_e32 v70, v70
	v_exp_f32_e32 v71, v71
	v_exp_f32_e32 v64, v64
	v_exp_f32_e32 v65, v65
	v_exp_f32_e32 v66, v66
	v_exp_f32_e32 v67, v67
	v_pk_add_f32 v[68:69], v[68:69], 1.0 op_sel_hi:[1,0]
	v_pk_add_f32 v[70:71], v[70:71], 1.0 op_sel_hi:[1,0]
	v_pk_add_f32 v[64:65], v[64:65], 1.0 op_sel_hi:[1,0]
	v_pk_add_f32 v[66:67], v[66:67], 1.0 op_sel_hi:[1,0]
	v_rcp_f32_e32 v68, v68
	v_rcp_f32_e32 v69, v69
	v_rcp_f32_e32 v70, v70
	v_rcp_f32_e32 v71, v71
	v_rcp_f32_e32 v64, v64
	v_rcp_f32_e32 v65, v65
	v_rcp_f32_e32 v66, v66
	v_rcp_f32_e32 v67, v67
	v_pk_fma_f32 v[68:69], v[68:69], s[20:21], 0.5 op_sel_hi:[1,0,0]
	v_pk_fma_f32 v[70:71], v[70:71], s[20:21], 0.5 op_sel_hi:[1,0,0]
	v_pk_fma_f32 v[64:65], v[64:65], s[20:21], 0.5 op_sel_hi:[1,0,0]
	v_pk_fma_f32 v[66:67], v[66:67], s[20:21], 0.5 op_sel_hi:[1,0,0]
	v_cvt_u32_f32_e32 v134, v68
	v_cvt_u32_f32_e32 v135, v64
	v_cvt_u32_f32_sdwa v134, v69 dst_sel:BYTE_1 dst_unused:UNUSED_PRESERVE src0_sel:DWORD
	v_cvt_u32_f32_sdwa v135, v65 dst_sel:BYTE_1 dst_unused:UNUSED_PRESERVE src0_sel:DWORD
	v_cvt_u32_f32_sdwa v134, v70 dst_sel:BYTE_2 dst_unused:UNUSED_PRESERVE src0_sel:DWORD
	v_cvt_u32_f32_sdwa v135, v66 dst_sel:BYTE_2 dst_unused:UNUSED_PRESERVE src0_sel:DWORD
	v_cvt_u32_f32_sdwa v134, v71 dst_sel:BYTE_3 dst_unused:UNUSED_PRESERVE src0_sel:DWORD
	v_cvt_u32_f32_sdwa v135, v67 dst_sel:BYTE_3 dst_unused:UNUSED_PRESERVE src0_sel:DWORD
	s_nop 0
	global_store_dwordx2 v155, v[134:135], s[4:5] offset:128
	v_pk_fma_f32 v[60:61], v[60:61], s[98:99], v[136:137] op_sel_hi:[1,0,1]
	v_pk_fma_f32 v[62:63], v[62:63], s[98:99], v[138:139] op_sel_hi:[1,0,1]
	v_pk_fma_f32 v[56:57], v[56:57], s[98:99], v[140:141] op_sel_hi:[1,0,1]
	v_pk_fma_f32 v[58:59], v[58:59], s[98:99], v[142:143] op_sel_hi:[1,0,1]
	v_exp_f32_e32 v60, v60
	v_exp_f32_e32 v61, v61
	v_exp_f32_e32 v62, v62
	v_exp_f32_e32 v63, v63
	v_exp_f32_e32 v56, v56
	v_exp_f32_e32 v57, v57
	v_exp_f32_e32 v58, v58
	v_exp_f32_e32 v59, v59
	v_pk_add_f32 v[60:61], v[60:61], 1.0 op_sel_hi:[1,0]
	v_pk_add_f32 v[62:63], v[62:63], 1.0 op_sel_hi:[1,0]
	v_pk_add_f32 v[56:57], v[56:57], 1.0 op_sel_hi:[1,0]
	v_pk_add_f32 v[58:59], v[58:59], 1.0 op_sel_hi:[1,0]
	v_rcp_f32_e32 v60, v60
	v_rcp_f32_e32 v61, v61
	v_rcp_f32_e32 v62, v62
	v_rcp_f32_e32 v63, v63
	v_rcp_f32_e32 v56, v56
	v_rcp_f32_e32 v57, v57
	v_rcp_f32_e32 v58, v58
	v_rcp_f32_e32 v59, v59
	v_pk_fma_f32 v[60:61], v[60:61], s[20:21], 0.5 op_sel_hi:[1,0,0]
	v_pk_fma_f32 v[62:63], v[62:63], s[20:21], 0.5 op_sel_hi:[1,0,0]
	v_pk_fma_f32 v[56:57], v[56:57], s[20:21], 0.5 op_sel_hi:[1,0,0]
	v_pk_fma_f32 v[58:59], v[58:59], s[20:21], 0.5 op_sel_hi:[1,0,0]
	v_cvt_u32_f32_e32 v160, v60
	v_cvt_u32_f32_e32 v161, v56
	v_cvt_u32_f32_sdwa v160, v61 dst_sel:BYTE_1 dst_unused:UNUSED_PRESERVE src0_sel:DWORD
	v_cvt_u32_f32_sdwa v161, v57 dst_sel:BYTE_1 dst_unused:UNUSED_PRESERVE src0_sel:DWORD
	v_cvt_u32_f32_sdwa v160, v62 dst_sel:BYTE_2 dst_unused:UNUSED_PRESERVE src0_sel:DWORD
	v_cvt_u32_f32_sdwa v161, v58 dst_sel:BYTE_2 dst_unused:UNUSED_PRESERVE src0_sel:DWORD
	v_cvt_u32_f32_sdwa v160, v63 dst_sel:BYTE_3 dst_unused:UNUSED_PRESERVE src0_sel:DWORD
	v_cvt_u32_f32_sdwa v161, v59 dst_sel:BYTE_3 dst_unused:UNUSED_PRESERVE src0_sel:DWORD
	s_nop 0
	global_store_dwordx2 v156, v[160:161], s[4:5]
	v_pk_fma_f32 v[52:53], v[52:53], s[98:99], v[144:145] op_sel_hi:[1,0,1]
	v_pk_fma_f32 v[54:55], v[54:55], s[98:99], v[146:147] op_sel_hi:[1,0,1]
	v_pk_fma_f32 v[48:49], v[48:49], s[98:99], v[148:149] op_sel_hi:[1,0,1]
	v_pk_fma_f32 v[50:51], v[50:51], s[98:99], v[150:151] op_sel_hi:[1,0,1]
	v_exp_f32_e32 v52, v52
	v_exp_f32_e32 v53, v53
	v_exp_f32_e32 v54, v54
	v_exp_f32_e32 v55, v55
	v_exp_f32_e32 v48, v48
	v_exp_f32_e32 v49, v49
	v_exp_f32_e32 v50, v50
	v_exp_f32_e32 v51, v51
	v_pk_add_f32 v[52:53], v[52:53], 1.0 op_sel_hi:[1,0]
	v_pk_add_f32 v[54:55], v[54:55], 1.0 op_sel_hi:[1,0]
	v_pk_add_f32 v[48:49], v[48:49], 1.0 op_sel_hi:[1,0]
	v_pk_add_f32 v[50:51], v[50:51], 1.0 op_sel_hi:[1,0]
	v_rcp_f32_e32 v52, v52
	v_rcp_f32_e32 v53, v53
	v_rcp_f32_e32 v54, v54
	v_rcp_f32_e32 v55, v55
	v_rcp_f32_e32 v48, v48
	v_rcp_f32_e32 v49, v49
	v_rcp_f32_e32 v50, v50
	v_rcp_f32_e32 v51, v51
	v_pk_fma_f32 v[52:53], v[52:53], s[20:21], 0.5 op_sel_hi:[1,0,0]
	v_pk_fma_f32 v[54:55], v[54:55], s[20:21], 0.5 op_sel_hi:[1,0,0]
	v_pk_fma_f32 v[48:49], v[48:49], s[20:21], 0.5 op_sel_hi:[1,0,0]
	v_pk_fma_f32 v[50:51], v[50:51], s[20:21], 0.5 op_sel_hi:[1,0,0]
	v_cvt_u32_f32_e32 v134, v52
	v_cvt_u32_f32_e32 v135, v48
	v_cvt_u32_f32_sdwa v134, v53 dst_sel:BYTE_1 dst_unused:UNUSED_PRESERVE src0_sel:DWORD
	v_cvt_u32_f32_sdwa v135, v49 dst_sel:BYTE_1 dst_unused:UNUSED_PRESERVE src0_sel:DWORD
	v_cvt_u32_f32_sdwa v134, v54 dst_sel:BYTE_2 dst_unused:UNUSED_PRESERVE src0_sel:DWORD
	v_cvt_u32_f32_sdwa v135, v50 dst_sel:BYTE_2 dst_unused:UNUSED_PRESERVE src0_sel:DWORD
	v_cvt_u32_f32_sdwa v134, v55 dst_sel:BYTE_3 dst_unused:UNUSED_PRESERVE src0_sel:DWORD
	v_cvt_u32_f32_sdwa v135, v51 dst_sel:BYTE_3 dst_unused:UNUSED_PRESERVE src0_sel:DWORD
	s_nop 0
	global_store_dwordx2 v156, v[134:135], s[4:5] offset:128
	v_pk_fma_f32 v[44:45], v[44:45], s[98:99], v[136:137] op_sel_hi:[1,0,1]
	v_pk_fma_f32 v[46:47], v[46:47], s[98:99], v[138:139] op_sel_hi:[1,0,1]
	v_pk_fma_f32 v[40:41], v[40:41], s[98:99], v[140:141] op_sel_hi:[1,0,1]
	v_pk_fma_f32 v[42:43], v[42:43], s[98:99], v[142:143] op_sel_hi:[1,0,1]
	v_exp_f32_e32 v44, v44
	v_exp_f32_e32 v45, v45
	v_exp_f32_e32 v46, v46
	v_exp_f32_e32 v47, v47
	v_exp_f32_e32 v40, v40
	v_exp_f32_e32 v41, v41
	v_exp_f32_e32 v42, v42
	v_exp_f32_e32 v43, v43
	v_pk_add_f32 v[44:45], v[44:45], 1.0 op_sel_hi:[1,0]
	v_pk_add_f32 v[46:47], v[46:47], 1.0 op_sel_hi:[1,0]
	v_pk_add_f32 v[40:41], v[40:41], 1.0 op_sel_hi:[1,0]
	v_pk_add_f32 v[42:43], v[42:43], 1.0 op_sel_hi:[1,0]
	v_rcp_f32_e32 v44, v44
	v_rcp_f32_e32 v45, v45
	v_rcp_f32_e32 v46, v46
	v_rcp_f32_e32 v47, v47
	v_rcp_f32_e32 v40, v40
	v_rcp_f32_e32 v41, v41
	v_rcp_f32_e32 v42, v42
	v_rcp_f32_e32 v43, v43
	v_pk_fma_f32 v[44:45], v[44:45], s[20:21], 0.5 op_sel_hi:[1,0,0]
	v_pk_fma_f32 v[46:47], v[46:47], s[20:21], 0.5 op_sel_hi:[1,0,0]
	v_pk_fma_f32 v[40:41], v[40:41], s[20:21], 0.5 op_sel_hi:[1,0,0]
	v_pk_fma_f32 v[42:43], v[42:43], s[20:21], 0.5 op_sel_hi:[1,0,0]
	v_cvt_u32_f32_e32 v160, v44
	v_cvt_u32_f32_e32 v161, v40
	v_cvt_u32_f32_sdwa v160, v45 dst_sel:BYTE_1 dst_unused:UNUSED_PRESERVE src0_sel:DWORD
	v_cvt_u32_f32_sdwa v161, v41 dst_sel:BYTE_1 dst_unused:UNUSED_PRESERVE src0_sel:DWORD
	v_cvt_u32_f32_sdwa v160, v46 dst_sel:BYTE_2 dst_unused:UNUSED_PRESERVE src0_sel:DWORD
	v_cvt_u32_f32_sdwa v161, v42 dst_sel:BYTE_2 dst_unused:UNUSED_PRESERVE src0_sel:DWORD
	v_cvt_u32_f32_sdwa v160, v47 dst_sel:BYTE_3 dst_unused:UNUSED_PRESERVE src0_sel:DWORD
	v_cvt_u32_f32_sdwa v161, v43 dst_sel:BYTE_3 dst_unused:UNUSED_PRESERVE src0_sel:DWORD
	s_nop 0
	global_store_dwordx2 v157, v[160:161], s[4:5]
	v_pk_fma_f32 v[36:37], v[36:37], s[98:99], v[144:145] op_sel_hi:[1,0,1]
	v_pk_fma_f32 v[38:39], v[38:39], s[98:99], v[146:147] op_sel_hi:[1,0,1]
	v_pk_fma_f32 v[32:33], v[32:33], s[98:99], v[148:149] op_sel_hi:[1,0,1]
	v_pk_fma_f32 v[34:35], v[34:35], s[98:99], v[150:151] op_sel_hi:[1,0,1]
	v_exp_f32_e32 v36, v36
	v_exp_f32_e32 v37, v37
	v_exp_f32_e32 v38, v38
	v_exp_f32_e32 v39, v39
	v_exp_f32_e32 v32, v32
	v_exp_f32_e32 v33, v33
	v_exp_f32_e32 v34, v34
	v_exp_f32_e32 v35, v35
	v_pk_add_f32 v[36:37], v[36:37], 1.0 op_sel_hi:[1,0]
	v_pk_add_f32 v[38:39], v[38:39], 1.0 op_sel_hi:[1,0]
	v_pk_add_f32 v[32:33], v[32:33], 1.0 op_sel_hi:[1,0]
	v_pk_add_f32 v[34:35], v[34:35], 1.0 op_sel_hi:[1,0]
	v_rcp_f32_e32 v36, v36
	v_rcp_f32_e32 v37, v37
	v_rcp_f32_e32 v38, v38
	v_rcp_f32_e32 v39, v39
	v_rcp_f32_e32 v32, v32
	v_rcp_f32_e32 v33, v33
	v_rcp_f32_e32 v34, v34
	v_rcp_f32_e32 v35, v35
	v_pk_fma_f32 v[36:37], v[36:37], s[20:21], 0.5 op_sel_hi:[1,0,0]
	v_pk_fma_f32 v[38:39], v[38:39], s[20:21], 0.5 op_sel_hi:[1,0,0]
	v_pk_fma_f32 v[32:33], v[32:33], s[20:21], 0.5 op_sel_hi:[1,0,0]
	v_pk_fma_f32 v[34:35], v[34:35], s[20:21], 0.5 op_sel_hi:[1,0,0]
	v_cvt_u32_f32_e32 v134, v36
	v_cvt_u32_f32_e32 v135, v32
	v_cvt_u32_f32_sdwa v134, v37 dst_sel:BYTE_1 dst_unused:UNUSED_PRESERVE src0_sel:DWORD
	v_cvt_u32_f32_sdwa v135, v33 dst_sel:BYTE_1 dst_unused:UNUSED_PRESERVE src0_sel:DWORD
	v_cvt_u32_f32_sdwa v134, v38 dst_sel:BYTE_2 dst_unused:UNUSED_PRESERVE src0_sel:DWORD
	v_cvt_u32_f32_sdwa v135, v34 dst_sel:BYTE_2 dst_unused:UNUSED_PRESERVE src0_sel:DWORD
	v_cvt_u32_f32_sdwa v134, v39 dst_sel:BYTE_3 dst_unused:UNUSED_PRESERVE src0_sel:DWORD
	v_cvt_u32_f32_sdwa v135, v35 dst_sel:BYTE_3 dst_unused:UNUSED_PRESERVE src0_sel:DWORD
	s_nop 0
	global_store_dwordx2 v157, v[134:135], s[4:5] offset:128
	v_pk_fma_f32 v[28:29], v[28:29], s[98:99], v[136:137] op_sel_hi:[1,0,1]
	v_pk_fma_f32 v[30:31], v[30:31], s[98:99], v[138:139] op_sel_hi:[1,0,1]
	v_pk_fma_f32 v[24:25], v[24:25], s[98:99], v[140:141] op_sel_hi:[1,0,1]
	v_pk_fma_f32 v[26:27], v[26:27], s[98:99], v[142:143] op_sel_hi:[1,0,1]
	v_exp_f32_e32 v28, v28
	v_exp_f32_e32 v29, v29
	v_exp_f32_e32 v30, v30
	v_exp_f32_e32 v31, v31
	v_exp_f32_e32 v24, v24
	v_exp_f32_e32 v25, v25
	v_exp_f32_e32 v26, v26
	v_exp_f32_e32 v27, v27
	v_pk_add_f32 v[28:29], v[28:29], 1.0 op_sel_hi:[1,0]
	v_pk_add_f32 v[30:31], v[30:31], 1.0 op_sel_hi:[1,0]
	v_pk_add_f32 v[24:25], v[24:25], 1.0 op_sel_hi:[1,0]
	v_pk_add_f32 v[26:27], v[26:27], 1.0 op_sel_hi:[1,0]
	v_rcp_f32_e32 v28, v28
	v_rcp_f32_e32 v29, v29
	v_rcp_f32_e32 v30, v30
	v_rcp_f32_e32 v31, v31
	v_rcp_f32_e32 v24, v24
	v_rcp_f32_e32 v25, v25
	v_rcp_f32_e32 v26, v26
	v_rcp_f32_e32 v27, v27
	v_pk_fma_f32 v[28:29], v[28:29], s[20:21], 0.5 op_sel_hi:[1,0,0]
	v_pk_fma_f32 v[30:31], v[30:31], s[20:21], 0.5 op_sel_hi:[1,0,0]
	v_pk_fma_f32 v[24:25], v[24:25], s[20:21], 0.5 op_sel_hi:[1,0,0]
	v_pk_fma_f32 v[26:27], v[26:27], s[20:21], 0.5 op_sel_hi:[1,0,0]
	v_cvt_u32_f32_e32 v160, v28
	v_cvt_u32_f32_e32 v161, v24
	v_cvt_u32_f32_sdwa v160, v29 dst_sel:BYTE_1 dst_unused:UNUSED_PRESERVE src0_sel:DWORD
	v_cvt_u32_f32_sdwa v161, v25 dst_sel:BYTE_1 dst_unused:UNUSED_PRESERVE src0_sel:DWORD
	v_cvt_u32_f32_sdwa v160, v30 dst_sel:BYTE_2 dst_unused:UNUSED_PRESERVE src0_sel:DWORD
	v_cvt_u32_f32_sdwa v161, v26 dst_sel:BYTE_2 dst_unused:UNUSED_PRESERVE src0_sel:DWORD
	v_cvt_u32_f32_sdwa v160, v31 dst_sel:BYTE_3 dst_unused:UNUSED_PRESERVE src0_sel:DWORD
	v_cvt_u32_f32_sdwa v161, v27 dst_sel:BYTE_3 dst_unused:UNUSED_PRESERVE src0_sel:DWORD
	s_nop 0
	global_store_dwordx2 v158, v[160:161], s[4:5]
	v_pk_fma_f32 v[20:21], v[20:21], s[98:99], v[144:145] op_sel_hi:[1,0,1]
	v_pk_fma_f32 v[22:23], v[22:23], s[98:99], v[146:147] op_sel_hi:[1,0,1]
	v_pk_fma_f32 v[16:17], v[16:17], s[98:99], v[148:149] op_sel_hi:[1,0,1]
	v_pk_fma_f32 v[18:19], v[18:19], s[98:99], v[150:151] op_sel_hi:[1,0,1]
	v_exp_f32_e32 v20, v20
	v_exp_f32_e32 v21, v21
	v_exp_f32_e32 v22, v22
	v_exp_f32_e32 v23, v23
	v_exp_f32_e32 v16, v16
	v_exp_f32_e32 v17, v17
	v_exp_f32_e32 v18, v18
	v_exp_f32_e32 v19, v19
	v_pk_add_f32 v[20:21], v[20:21], 1.0 op_sel_hi:[1,0]
	v_pk_add_f32 v[22:23], v[22:23], 1.0 op_sel_hi:[1,0]
	v_pk_add_f32 v[16:17], v[16:17], 1.0 op_sel_hi:[1,0]
	v_pk_add_f32 v[18:19], v[18:19], 1.0 op_sel_hi:[1,0]
	v_rcp_f32_e32 v20, v20
	v_rcp_f32_e32 v21, v21
	v_rcp_f32_e32 v22, v22
	v_rcp_f32_e32 v23, v23
	v_rcp_f32_e32 v16, v16
	v_rcp_f32_e32 v17, v17
	v_rcp_f32_e32 v18, v18
	v_rcp_f32_e32 v19, v19
	v_pk_fma_f32 v[20:21], v[20:21], s[20:21], 0.5 op_sel_hi:[1,0,0]
	v_pk_fma_f32 v[22:23], v[22:23], s[20:21], 0.5 op_sel_hi:[1,0,0]
	v_pk_fma_f32 v[16:17], v[16:17], s[20:21], 0.5 op_sel_hi:[1,0,0]
	v_pk_fma_f32 v[18:19], v[18:19], s[20:21], 0.5 op_sel_hi:[1,0,0]
	v_cvt_u32_f32_e32 v134, v20
	v_cvt_u32_f32_e32 v135, v16
	v_cvt_u32_f32_sdwa v134, v21 dst_sel:BYTE_1 dst_unused:UNUSED_PRESERVE src0_sel:DWORD
	v_cvt_u32_f32_sdwa v135, v17 dst_sel:BYTE_1 dst_unused:UNUSED_PRESERVE src0_sel:DWORD
	v_cvt_u32_f32_sdwa v134, v22 dst_sel:BYTE_2 dst_unused:UNUSED_PRESERVE src0_sel:DWORD
	v_cvt_u32_f32_sdwa v135, v18 dst_sel:BYTE_2 dst_unused:UNUSED_PRESERVE src0_sel:DWORD
	v_cvt_u32_f32_sdwa v134, v23 dst_sel:BYTE_3 dst_unused:UNUSED_PRESERVE src0_sel:DWORD
	v_cvt_u32_f32_sdwa v135, v19 dst_sel:BYTE_3 dst_unused:UNUSED_PRESERVE src0_sel:DWORD
	s_nop 0
	global_store_dwordx2 v158, v[134:135], s[4:5] offset:128
	v_pk_fma_f32 v[12:13], v[12:13], s[98:99], v[136:137] op_sel_hi:[1,0,1]
	v_pk_fma_f32 v[14:15], v[14:15], s[98:99], v[138:139] op_sel_hi:[1,0,1]
	v_pk_fma_f32 v[8:9], v[8:9], s[98:99], v[140:141] op_sel_hi:[1,0,1]
	v_pk_fma_f32 v[10:11], v[10:11], s[98:99], v[142:143] op_sel_hi:[1,0,1]
	v_exp_f32_e32 v12, v12
	v_exp_f32_e32 v13, v13
	v_exp_f32_e32 v14, v14
	v_exp_f32_e32 v15, v15
	v_exp_f32_e32 v8, v8
	v_exp_f32_e32 v9, v9
	v_exp_f32_e32 v10, v10
	v_exp_f32_e32 v11, v11
	v_pk_add_f32 v[12:13], v[12:13], 1.0 op_sel_hi:[1,0]
	v_pk_add_f32 v[14:15], v[14:15], 1.0 op_sel_hi:[1,0]
	v_pk_add_f32 v[8:9], v[8:9], 1.0 op_sel_hi:[1,0]
	v_pk_add_f32 v[10:11], v[10:11], 1.0 op_sel_hi:[1,0]
	v_rcp_f32_e32 v12, v12
	v_rcp_f32_e32 v13, v13
	v_rcp_f32_e32 v14, v14
	v_rcp_f32_e32 v15, v15
	v_rcp_f32_e32 v8, v8
	v_rcp_f32_e32 v9, v9
	v_rcp_f32_e32 v10, v10
	v_rcp_f32_e32 v11, v11
	v_pk_fma_f32 v[12:13], v[12:13], s[20:21], 0.5 op_sel_hi:[1,0,0]
	v_pk_fma_f32 v[14:15], v[14:15], s[20:21], 0.5 op_sel_hi:[1,0,0]
	v_pk_fma_f32 v[8:9], v[8:9], s[20:21], 0.5 op_sel_hi:[1,0,0]
	v_pk_fma_f32 v[10:11], v[10:11], s[20:21], 0.5 op_sel_hi:[1,0,0]
	v_cvt_u32_f32_e32 v160, v12
	v_cvt_u32_f32_e32 v161, v8
	v_cvt_u32_f32_sdwa v160, v13 dst_sel:BYTE_1 dst_unused:UNUSED_PRESERVE src0_sel:DWORD
	v_cvt_u32_f32_sdwa v161, v9 dst_sel:BYTE_1 dst_unused:UNUSED_PRESERVE src0_sel:DWORD
	v_cvt_u32_f32_sdwa v160, v14 dst_sel:BYTE_2 dst_unused:UNUSED_PRESERVE src0_sel:DWORD
	v_cvt_u32_f32_sdwa v161, v10 dst_sel:BYTE_2 dst_unused:UNUSED_PRESERVE src0_sel:DWORD
	v_cvt_u32_f32_sdwa v160, v15 dst_sel:BYTE_3 dst_unused:UNUSED_PRESERVE src0_sel:DWORD
	v_cvt_u32_f32_sdwa v161, v11 dst_sel:BYTE_3 dst_unused:UNUSED_PRESERVE src0_sel:DWORD
	s_nop 0
	global_store_dwordx2 v159, v[160:161], s[4:5]
	v_pk_fma_f32 v[4:5], v[4:5], s[98:99], v[144:145] op_sel_hi:[1,0,1]
	v_pk_fma_f32 v[6:7], v[6:7], s[98:99], v[146:147] op_sel_hi:[1,0,1]
	v_pk_fma_f32 v[0:1], v[0:1], s[98:99], v[148:149] op_sel_hi:[1,0,1]
	v_pk_fma_f32 v[2:3], v[2:3], s[98:99], v[150:151] op_sel_hi:[1,0,1]
	v_exp_f32_e32 v4, v4
	v_exp_f32_e32 v5, v5
	v_exp_f32_e32 v6, v6
	v_exp_f32_e32 v7, v7
	v_exp_f32_e32 v0, v0
	v_exp_f32_e32 v1, v1
	v_exp_f32_e32 v2, v2
	v_exp_f32_e32 v3, v3
	v_pk_add_f32 v[4:5], v[4:5], 1.0 op_sel_hi:[1,0]
	v_pk_add_f32 v[6:7], v[6:7], 1.0 op_sel_hi:[1,0]
	v_pk_add_f32 v[0:1], v[0:1], 1.0 op_sel_hi:[1,0]
	v_pk_add_f32 v[2:3], v[2:3], 1.0 op_sel_hi:[1,0]
	v_rcp_f32_e32 v4, v4
	v_rcp_f32_e32 v5, v5
	v_rcp_f32_e32 v6, v6
	v_rcp_f32_e32 v7, v7
	v_rcp_f32_e32 v0, v0
	v_rcp_f32_e32 v1, v1
	v_rcp_f32_e32 v2, v2
	v_rcp_f32_e32 v3, v3
	v_pk_fma_f32 v[4:5], v[4:5], s[20:21], 0.5 op_sel_hi:[1,0,0]
	v_pk_fma_f32 v[6:7], v[6:7], s[20:21], 0.5 op_sel_hi:[1,0,0]
	v_pk_fma_f32 v[0:1], v[0:1], s[20:21], 0.5 op_sel_hi:[1,0,0]
	v_pk_fma_f32 v[2:3], v[2:3], s[20:21], 0.5 op_sel_hi:[1,0,0]
	v_cvt_u32_f32_e32 v134, v4
	v_cvt_u32_f32_e32 v135, v0
	v_cvt_u32_f32_sdwa v134, v5 dst_sel:BYTE_1 dst_unused:UNUSED_PRESERVE src0_sel:DWORD
	v_cvt_u32_f32_sdwa v135, v1 dst_sel:BYTE_1 dst_unused:UNUSED_PRESERVE src0_sel:DWORD
	v_cvt_u32_f32_sdwa v134, v6 dst_sel:BYTE_2 dst_unused:UNUSED_PRESERVE src0_sel:DWORD
	v_cvt_u32_f32_sdwa v135, v2 dst_sel:BYTE_2 dst_unused:UNUSED_PRESERVE src0_sel:DWORD
	v_cvt_u32_f32_sdwa v134, v7 dst_sel:BYTE_3 dst_unused:UNUSED_PRESERVE src0_sel:DWORD
	v_cvt_u32_f32_sdwa v135, v3 dst_sel:BYTE_3 dst_unused:UNUSED_PRESERVE src0_sel:DWORD
	s_nop 0
	global_store_dwordx2 v159, v[134:135], s[4:5] offset:128
	s_mov_b64 s[4:5], 0
